# phase-2 rg items: LA/LI LDS arrays XOR-swizzled (granule ^= row&3) so the gate-result ds_write_b128 go from 8-way to 2-way bank conflicts; stacked on all earlier edits
# baseline (speedup 1.0000x reference)
.LBB0_266:
	s_waitcnt vmcnt(0)
	v_cmp_gt_u32_e64 s[98:99], s45, v204
	v_mul_f32_e32 v240, 0xc1000000, v92
	v_mul_f32_e32 v241, 0xc1000000, v93
	v_mul_f32_e32 v242, 0xc1000000, v94
	v_mul_f32_e32 v243, 0xc1000000, v95
	v_mul_f32_e32 v244, 0xc1000000, v96
	v_mul_f32_e32 v245, 0xc1000000, v97
	v_mul_f32_e32 v246, 0xc1000000, v98
	v_mul_f32_e32 v247, 0xc1000000, v99
	v_cndmask_b32_e64 v240, 1.0, v240, s[98:99]
	v_cndmask_b32_e64 v241, 1.0, v241, s[98:99]
	v_cndmask_b32_e64 v242, 1.0, v242, s[98:99]
	v_cndmask_b32_e64 v243, 1.0, v243, s[98:99]
	v_cndmask_b32_e64 v244, 1.0, v244, s[98:99]
	v_cndmask_b32_e64 v245, 1.0, v245, s[98:99]
	v_cndmask_b32_e64 v246, 1.0, v246, s[98:99]
	v_cndmask_b32_e64 v247, 1.0, v247, s[98:99]
	v_and_b32_e32 v186, 63, v204
	v_bfe_u32 v187, v204, 6, 1
	v_lshl_or_b32 v186, v187, 12, v186
	v_mul_u32_u24_e32 v187, 63, v187
	v_lshrrev_b32_e32 v188, 7, v204
	v_lshlrev_b32_e32 v188, 4, v188
	v_or_b32_e32 v170, 0, v188
	v_xor_b32_e32 v170, v187, v170
	v_and_b32_e32 v189, 3, v170
	v_lshlrev_b32_e32 v189, 4, v189
	v_lshl_add_u32 v170, v170, 6, v186
	v_lshlrev_b32_e32 v170, 2, v170
	v_xor_b32_e32 v170, v189, v170
	v_or_b32_e32 v171, 1, v188
	v_xor_b32_e32 v171, v187, v171
	v_and_b32_e32 v189, 3, v171
	v_lshlrev_b32_e32 v189, 4, v189
	v_lshl_add_u32 v171, v171, 6, v186
	v_lshlrev_b32_e32 v171, 2, v171
	v_xor_b32_e32 v171, v189, v171
	v_or_b32_e32 v172, 2, v188
	v_xor_b32_e32 v172, v187, v172
	v_and_b32_e32 v189, 3, v172
	v_lshlrev_b32_e32 v189, 4, v189
	v_lshl_add_u32 v172, v172, 6, v186
	v_lshlrev_b32_e32 v172, 2, v172
	v_xor_b32_e32 v172, v189, v172
	v_or_b32_e32 v173, 3, v188
	v_xor_b32_e32 v173, v187, v173
	v_and_b32_e32 v189, 3, v173
	v_lshlrev_b32_e32 v189, 4, v189
	v_lshl_add_u32 v173, v173, 6, v186
	v_lshlrev_b32_e32 v173, 2, v173
	v_xor_b32_e32 v173, v189, v173
	v_or_b32_e32 v174, 4, v188
	v_xor_b32_e32 v174, v187, v174
	v_and_b32_e32 v189, 3, v174
	v_lshlrev_b32_e32 v189, 4, v189
	v_lshl_add_u32 v174, v174, 6, v186
	v_lshlrev_b32_e32 v174, 2, v174
	v_xor_b32_e32 v174, v189, v174
	v_or_b32_e32 v175, 5, v188
	v_xor_b32_e32 v175, v187, v175
	v_and_b32_e32 v189, 3, v175
	v_lshlrev_b32_e32 v189, 4, v189
	v_lshl_add_u32 v175, v175, 6, v186
	v_lshlrev_b32_e32 v175, 2, v175
	v_xor_b32_e32 v175, v189, v175
	v_or_b32_e32 v176, 6, v188
	v_xor_b32_e32 v176, v187, v176
	v_and_b32_e32 v189, 3, v176
	v_lshlrev_b32_e32 v189, 4, v189
	v_lshl_add_u32 v176, v176, 6, v186
	v_lshlrev_b32_e32 v176, 2, v176
	v_xor_b32_e32 v176, v189, v176
	v_or_b32_e32 v177, 7, v188
	v_xor_b32_e32 v177, v187, v177
	v_and_b32_e32 v189, 3, v177
	v_lshlrev_b32_e32 v189, 4, v189
	v_lshl_add_u32 v177, v177, 6, v186
	v_lshlrev_b32_e32 v177, 2, v177
	v_xor_b32_e32 v177, v189, v177
	v_or_b32_e32 v178, 8, v188
	v_xor_b32_e32 v178, v187, v178
	v_and_b32_e32 v189, 3, v178
	v_lshlrev_b32_e32 v189, 4, v189
	v_lshl_add_u32 v178, v178, 6, v186
	v_lshlrev_b32_e32 v178, 2, v178
	v_xor_b32_e32 v178, v189, v178
	v_or_b32_e32 v179, 9, v188
	v_xor_b32_e32 v179, v187, v179
	v_and_b32_e32 v189, 3, v179
	v_lshlrev_b32_e32 v189, 4, v189
	v_lshl_add_u32 v179, v179, 6, v186
	v_lshlrev_b32_e32 v179, 2, v179
	v_xor_b32_e32 v179, v189, v179
	v_or_b32_e32 v180, 10, v188
	v_xor_b32_e32 v180, v187, v180
	v_and_b32_e32 v189, 3, v180
	v_lshlrev_b32_e32 v189, 4, v189
	v_lshl_add_u32 v180, v180, 6, v186
	v_lshlrev_b32_e32 v180, 2, v180
	v_xor_b32_e32 v180, v189, v180
	v_or_b32_e32 v181, 11, v188
	v_xor_b32_e32 v181, v187, v181
	v_and_b32_e32 v189, 3, v181
	v_lshlrev_b32_e32 v189, 4, v189
	v_lshl_add_u32 v181, v181, 6, v186
	v_lshlrev_b32_e32 v181, 2, v181
	v_xor_b32_e32 v181, v189, v181
	v_or_b32_e32 v182, 12, v188
	v_xor_b32_e32 v182, v187, v182
	v_and_b32_e32 v189, 3, v182
	v_lshlrev_b32_e32 v189, 4, v189
	v_lshl_add_u32 v182, v182, 6, v186
	v_lshlrev_b32_e32 v182, 2, v182
	v_xor_b32_e32 v182, v189, v182
	v_or_b32_e32 v183, 13, v188
	v_xor_b32_e32 v183, v187, v183
	v_and_b32_e32 v189, 3, v183
	v_lshlrev_b32_e32 v189, 4, v189
	v_lshl_add_u32 v183, v183, 6, v186
	v_lshlrev_b32_e32 v183, 2, v183
	v_xor_b32_e32 v183, v189, v183
	v_or_b32_e32 v184, 14, v188
	v_xor_b32_e32 v184, v187, v184
	v_and_b32_e32 v189, 3, v184
	v_lshlrev_b32_e32 v189, 4, v189
	v_lshl_add_u32 v184, v184, 6, v186
	v_lshlrev_b32_e32 v184, 2, v184
	v_xor_b32_e32 v184, v189, v184
	v_or_b32_e32 v185, 15, v188
	v_xor_b32_e32 v185, v187, v185
	v_and_b32_e32 v189, 3, v185
	v_lshlrev_b32_e32 v189, 4, v189
	v_lshl_add_u32 v185, v185, 6, v186
	v_lshlrev_b32_e32 v185, 2, v185
	v_xor_b32_e32 v185, v189, v185
	v_and_b32_e32 v200, 0x30, v204
	v_and_b32_e32 v201, 3, v204
	v_lshlrev_b32_e32 v201, 4, v201
	v_mov_b32_e32 v68, 0
	s_mov_b32 s10, s94
	s_mov_b32 s11, s3
	s_mov_b32 s69, s97
	v_mov_b32_e32 v69, v68
	v_mov_b32_e32 v70, v68
	v_mov_b32_e32 v71, v68
	v_mov_b32_e32 v72, v68
	v_mov_b32_e32 v73, v68
	v_mov_b32_e32 v74, v68
	v_mov_b32_e32 v75, v68
	v_mov_b32_e32 v100, v68
	v_mov_b32_e32 v101, v68
	v_mov_b32_e32 v102, v68
	v_mov_b32_e32 v103, v68
	v_mov_b32_e32 v104, v68
	v_mov_b32_e32 v105, v68
	v_mov_b32_e32 v106, v68
	v_mov_b32_e32 v107, v68
	s_branch .LBB0_269

.LBB0_281:
	v_mov_b32_e32 v0, v204
	s_nop 0
	v_and_b32_e32 v3, 0xffff0000, v40
	v_lshlrev_b32_e32 v2, 3, v0
	v_and_b32_e32 v116, 56, v2
	v_lshlrev_b32_e32 v2, 16, v40
	v_pk_fma_f32 v[2:3], v[32:33], v[2:3], v[48:49]
	v_lshlrev_b32_e32 v108, 16, v24
	v_and_b32_e32 v109, 0xffff0000, v24
	v_pk_fma_f32 v[2:3], v[8:9], v[108:109], v[2:3]
	v_lshlrev_b32_e32 v108, 16, v52
	v_and_b32_e32 v109, 0xffff0000, v52
	v_pk_fma_f32 v[2:3], v[12:13], v[108:109], v[2:3]
	v_lshlrev_b32_e32 v108, 16, v56
	v_and_b32_e32 v109, 0xffff0000, v56
	v_pk_fma_f32 v[108:109], v[16:17], v[108:109], v[2:3]
	v_lshlrev_b32_e32 v2, 16, v42
	v_and_b32_e32 v3, 0xffff0000, v42
	v_pk_fma_f32 v[2:3], v[28:29], v[2:3], v[44:45]
	v_lshlrev_b32_e32 v110, 16, v26
	v_and_b32_e32 v111, 0xffff0000, v26
	v_pk_fma_f32 v[2:3], v[4:5], v[110:111], v[2:3]
	v_lshlrev_b32_e32 v110, 16, v54
	v_and_b32_e32 v111, 0xffff0000, v54
	v_pk_fma_f32 v[2:3], v[20:21], v[110:111], v[2:3]
	v_lshlrev_b32_e32 v110, 16, v58
	v_and_b32_e32 v111, 0xffff0000, v58
	v_pk_fma_f32 v[112:113], v[36:37], v[110:111], v[2:3]
	v_lshlrev_b32_e32 v2, 16, v41
	v_and_b32_e32 v3, 0xffff0000, v41
	v_pk_fma_f32 v[2:3], v[34:35], v[2:3], v[50:51]
	v_lshlrev_b32_e32 v110, 16, v25
	v_and_b32_e32 v111, 0xffff0000, v25
	v_pk_fma_f32 v[2:3], v[10:11], v[110:111], v[2:3]
	v_lshlrev_b32_e32 v110, 16, v53
	v_and_b32_e32 v111, 0xffff0000, v53
	v_pk_fma_f32 v[2:3], v[14:15], v[110:111], v[2:3]
	v_lshlrev_b32_e32 v110, 16, v57
	v_and_b32_e32 v111, 0xffff0000, v57
	v_pk_fma_f32 v[110:111], v[18:19], v[110:111], v[2:3]
	v_lshlrev_b32_e32 v2, 16, v43
	v_and_b32_e32 v3, 0xffff0000, v43
	v_pk_fma_f32 v[2:3], v[30:31], v[2:3], v[46:47]
	v_lshlrev_b32_e32 v114, 16, v27
	v_and_b32_e32 v115, 0xffff0000, v27
	v_pk_fma_f32 v[2:3], v[6:7], v[114:115], v[2:3]
	v_lshlrev_b32_e32 v114, 16, v55
	v_and_b32_e32 v115, 0xffff0000, v55
	v_pk_fma_f32 v[2:3], v[22:23], v[114:115], v[2:3]
	v_lshlrev_b32_e32 v114, 16, v59
	v_and_b32_e32 v115, 0xffff0000, v59
	v_pk_fma_f32 v[114:115], v[38:39], v[114:115], v[2:3]
	v_ashrrev_i32_e32 v3, 3, v0
	v_lshl_add_u32 v117, v3, 8, 0
	v_lshl_add_u32 v118, v116, 2, v117
	ds_write_b128 v118, v[108:111]
	ds_write_b128 v118, v[112:115] offset:16
	v_cvt_pk_bf16_f32 v108, v108, v109
	v_cvt_pk_bf16_f32 v109, v110, v111
	v_cvt_pk_bf16_f32 v110, v112, v113
	v_mul_lo_u32 v3, v3, s67
	v_lshlrev_b32_e32 v112, 1, v116
	v_and_b32_e32 v127, 15, v0
	v_cvt_pk_bf16_f32 v111, v114, v115
	v_add3_u32 v3, v117, v3, v112
	v_and_b32_e32 v2, 48, v0
	ds_write_b128 v3, v[108:111] offset:16384
	v_mul_u32_u24_e32 v3, 0x90, v127
	v_add3_u32 v3, 0, v2, v3
	s_waitcnt lgkmcnt(0)
	s_barrier
	ds_read_b128 v[108:111], v3 offset:16384
	ds_read_b128 v[112:115], v3 offset:16448
	ds_read_b128 v[120:123], v3 offset:18688
	ds_read_b128 v[128:131], v3 offset:18752
	s_waitcnt lgkmcnt(1)
	v_mfma_f32_16x16x32_bf16 v[132:135], v[60:63], v[120:123], 0
	s_add_i32 s2, 0, 0xe400
	v_cmp_gt_u32_e32 vcc, s45, v0
	v_lshlrev_b32_e32 v127, 8, v127
	v_mfma_f32_16x16x32_bf16 v[136:139], v[76:79], v[120:123], 0
	ds_read_b128 v[120:123], v3 offset:20992
	ds_read_b128 v[140:143], v3 offset:21056
	v_mfma_f32_16x16x32_bf16 v[116:119], v[60:63], v[108:111], 0
	v_mfma_f32_16x16x32_bf16 v[108:111], v[76:79], v[108:111], 0
	s_waitcnt lgkmcnt(1)
	v_mfma_f32_16x16x32_bf16 v[144:147], v[60:63], v[120:123], 0
	v_mfma_f32_16x16x32_bf16 v[148:151], v[76:79], v[120:123], 0
	ds_read_b128 v[120:123], v3 offset:23296
	ds_read_b128 v[154:157], v3 offset:23360
	v_mov_b32_e32 v3, s2
	v_mfma_f32_16x16x32_bf16 v[166:169], v[64:67], v[112:115], v[116:119]
	s_waitcnt lgkmcnt(1)
	v_mfma_f32_16x16x32_bf16 v[158:161], v[60:63], v[120:123], 0
	v_mfma_f32_16x16x32_bf16 v[162:165], v[76:79], v[120:123], 0
	v_mfma_f32_16x16x32_bf16 v[120:123], v[80:83], v[112:115], v[108:111]
	v_mfma_f32_16x16x32_bf16 v[132:135], v[64:67], v[128:131], v[132:135]
	v_mfma_f32_16x16x32_bf16 v[116:119], v[80:83], v[128:131], v[136:139]
	s_nop 5
	v_add_f32_e32 v122, v90, v122
	v_mul_f32_e32 v122, 0xbfb8aa3b, v122
	v_exp_f32_e32 v122, v122
	v_mfma_f32_16x16x32_bf16 v[128:131], v[64:67], v[140:143], v[144:147]
	v_add_f32_e32 v123, v91, v123
	v_mul_f32_e32 v123, 0xbfb8aa3b, v123
	v_exp_f32_e32 v123, v123
	v_mfma_f32_16x16x32_bf16 v[112:115], v[80:83], v[140:143], v[148:151]
	v_mov_b32_e32 v140, s73
	v_cndmask_b32_e32 v3, v3, v140, vcc
	v_lshlrev_b32_e32 v140, 7, v0
	v_and_b32_e32 v140, 0x4000, v140
	v_add3_u32 v3, v3, v140, v127
	v_add_f32_e32 v140, v84, v166
	v_mul_f32_e32 v140, 0xbfb8aa3b, v140
	v_add_f32_e32 v141, v85, v167
	v_exp_f32_e32 v140, v140
	v_mul_f32_e32 v141, 0xbfb8aa3b, v141
	v_exp_f32_e32 v141, v141
	v_lshlrev_b32_e32 v127, 1, v0
	v_and_b32_e32 v127, 0x80, v127
	v_add_f32_e32 v140, 1.0, v140
	v_rcp_f32_e32 v140, v140
	v_add3_u32 v2, v3, v127, v2
	v_xor_b32_e32 v2, v201, v2
	v_add_f32_e32 v3, 1.0, v141
	v_add_f32_e32 v141, v86, v168
	v_mul_f32_e32 v141, 0xbfb8aa3b, v141
	v_rcp_f32_e32 v3, v3
	v_exp_f32_e32 v141, v141
	v_add_f32_e32 v142, v87, v169
	v_mul_f32_e32 v142, 0xbfb8aa3b, v142

	v_exp_f32_e32 v142, v142

	v_mul_f32_e32 v140, v240, v140

	v_add_f32_e32 v141, 1.0, v141

	v_rcp_f32_e32 v143, v141
	v_mul_f32_e32 v141, v241, v3
	v_add_f32_e32 v3, 1.0, v142
	v_rcp_f32_e32 v3, v3


	v_mul_f32_e32 v142, v242, v143


	v_mul_f32_e32 v143, v243, v3
	v_add_f32_e32 v3, v84, v132
	v_mul_f32_e32 v3, 0xbfb8aa3b, v3
	v_exp_f32_e32 v3, v3
	v_add_f32_e32 v127, v85, v133
	v_mul_f32_e32 v127, 0xbfb8aa3b, v127
	v_exp_f32_e32 v127, v127
	v_add_f32_e32 v3, 1.0, v3
	v_rcp_f32_e32 v3, v3
	v_add_f32_e32 v133, v86, v134
	v_add_f32_e32 v127, 1.0, v127
	v_mul_f32_e32 v133, 0xbfb8aa3b, v133
	v_rcp_f32_e32 v127, v127
	v_exp_f32_e32 v133, v133
	v_add_f32_e32 v134, v87, v135
	v_mul_f32_e32 v134, 0xbfb8aa3b, v134

	v_exp_f32_e32 v134, v134

	v_mul_f32_e32 v132, v240, v3

	v_add_f32_e32 v133, 1.0, v133

	v_rcp_f32_e32 v135, v133
	v_mul_f32_e32 v133, v241, v127
	v_add_f32_e32 v3, 1.0, v134
	v_rcp_f32_e32 v3, v3


	v_mul_f32_e32 v134, v242, v135


	v_mul_f32_e32 v135, v243, v3
	v_add_f32_e32 v3, v84, v128
	v_mul_f32_e32 v3, 0xbfb8aa3b, v3
	v_exp_f32_e32 v3, v3
	v_add_f32_e32 v127, v85, v129
	v_mul_f32_e32 v127, 0xbfb8aa3b, v127
	v_exp_f32_e32 v127, v127
	v_add_f32_e32 v3, 1.0, v3
	v_rcp_f32_e32 v3, v3
	v_add_f32_e32 v129, v86, v130
	v_add_f32_e32 v127, 1.0, v127
	v_mul_f32_e32 v129, 0xbfb8aa3b, v129
	v_rcp_f32_e32 v127, v127
	v_exp_f32_e32 v129, v129
	v_add_f32_e32 v130, v87, v131
	v_mul_f32_e32 v130, 0xbfb8aa3b, v130

	v_exp_f32_e32 v130, v130

	v_mul_f32_e32 v128, v240, v3

	v_add_f32_e32 v129, 1.0, v129

	v_rcp_f32_e32 v131, v129
	v_mul_f32_e32 v129, v241, v127
	v_add_f32_e32 v3, 1.0, v130
	v_rcp_f32_e32 v3, v3
	s_waitcnt lgkmcnt(0)
	v_mfma_f32_16x16x32_bf16 v[136:139], v[64:67], v[154:157], v[158:161]
	ds_write_b128 v2, v[140:143]
	ds_write_b128 v2, v[132:135] offset:4096


	v_mul_f32_e32 v130, v242, v131


	v_mul_f32_e32 v131, v243, v3
	s_nop 1
	s_nop 3
	v_add_f32_e32 v3, v84, v136
	v_mul_f32_e32 v3, 0xbfb8aa3b, v3
	v_exp_f32_e32 v3, v3
	v_add_f32_e32 v127, v85, v137
	v_mul_f32_e32 v127, 0xbfb8aa3b, v127
	v_exp_f32_e32 v127, v127
	v_add_f32_e32 v3, 1.0, v3
	v_rcp_f32_e32 v3, v3
	ds_write_b128 v2, v[128:131] offset:8192
	v_add_f32_e32 v129, v86, v138
	v_add_f32_e32 v127, 1.0, v127
	v_mul_f32_e32 v129, 0xbfb8aa3b, v129
	v_rcp_f32_e32 v127, v127
	v_exp_f32_e32 v129, v129
	v_add_f32_e32 v130, v87, v139
	v_mul_f32_e32 v130, 0xbfb8aa3b, v130

	v_exp_f32_e32 v130, v130

	v_mul_f32_e32 v128, v240, v3

	v_add_f32_e32 v129, 1.0, v129

	v_rcp_f32_e32 v131, v129
	v_mul_f32_e32 v129, v241, v127
	v_add_f32_e32 v3, 1.0, v130
	v_rcp_f32_e32 v3, v3


	v_mul_f32_e32 v130, v242, v131


	v_mul_f32_e32 v131, v243, v3
	v_add_f32_e32 v3, v88, v120
	ds_write_b128 v2, v[128:131] offset:12288
	v_mul_f32_e32 v3, 0xbfb8aa3b, v3
	v_exp_f32_e32 v3, v3
	v_add_f32_e32 v120, v89, v121
	v_mul_f32_e32 v120, 0xbfb8aa3b, v120
	v_exp_f32_e32 v120, v120
	v_add_f32_e32 v3, 1.0, v3
	v_rcp_f32_e32 v3, v3
	v_add_f32_e32 v122, 1.0, v122
	v_add_f32_e32 v120, 1.0, v120
	v_rcp_f32_e32 v121, v120


	v_mul_f32_e32 v120, v244, v3


	v_rcp_f32_e32 v122, v122
	v_mul_f32_e32 v121, v245, v121
	v_add_f32_e32 v3, 1.0, v123
	v_rcp_f32_e32 v3, v3


	v_mul_f32_e32 v122, v246, v122


	v_mul_f32_e32 v123, v247, v3
	v_add_f32_e32 v3, v88, v116
	ds_write_b128 v2, v[120:123] offset:64
	v_mul_f32_e32 v3, 0xbfb8aa3b, v3
	v_exp_f32_e32 v3, v3
	v_add_f32_e32 v116, v89, v117
	v_mul_f32_e32 v116, 0xbfb8aa3b, v116
	v_exp_f32_e32 v116, v116
	v_add_f32_e32 v3, 1.0, v3
	v_rcp_f32_e32 v3, v3
	v_add_f32_e32 v118, v90, v118
	v_add_f32_e32 v116, 1.0, v116
	v_mul_f32_e32 v118, 0xbfb8aa3b, v118
	v_rcp_f32_e32 v117, v116
	v_exp_f32_e32 v118, v118
	v_add_f32_e32 v119, v91, v119
	v_mul_f32_e32 v119, 0xbfb8aa3b, v119

	v_exp_f32_e32 v119, v119

	v_mul_f32_e32 v116, v244, v3

	v_add_f32_e32 v118, 1.0, v118

	v_rcp_f32_e32 v118, v118
	v_mul_f32_e32 v117, v245, v117
	v_add_f32_e32 v3, 1.0, v119
	v_rcp_f32_e32 v3, v3


	v_mul_f32_e32 v118, v246, v118


	v_mul_f32_e32 v119, v247, v3
	v_add_f32_e32 v3, v88, v112
	ds_write_b128 v2, v[116:119] offset:4160
	v_mul_f32_e32 v3, 0xbfb8aa3b, v3
	v_exp_f32_e32 v3, v3
	v_add_f32_e32 v112, v89, v113
	v_mul_f32_e32 v112, 0xbfb8aa3b, v112
	v_exp_f32_e32 v112, v112
	v_add_f32_e32 v3, 1.0, v3
	v_rcp_f32_e32 v3, v3
	v_add_f32_e32 v114, v90, v114
	v_add_f32_e32 v112, 1.0, v112
	v_mul_f32_e32 v114, 0xbfb8aa3b, v114
	v_rcp_f32_e32 v113, v112
	v_exp_f32_e32 v114, v114
	v_add_f32_e32 v115, v91, v115
	v_mul_f32_e32 v115, 0xbfb8aa3b, v115

	v_exp_f32_e32 v115, v115

	v_mul_f32_e32 v112, v244, v3

	v_add_f32_e32 v114, 1.0, v114

	v_rcp_f32_e32 v114, v114
	v_mul_f32_e32 v113, v245, v113
	v_add_f32_e32 v3, 1.0, v115
	v_rcp_f32_e32 v3, v3
	v_mfma_f32_16x16x32_bf16 v[108:111], v[80:83], v[154:157], v[162:165]


	v_mul_f32_e32 v114, v246, v114


	v_mul_f32_e32 v115, v247, v3
	s_nop 1
	ds_write_b128 v2, v[112:115] offset:8256
	s_nop 3
	v_add_f32_e32 v3, v88, v108
	v_mul_f32_e32 v3, 0xbfb8aa3b, v3
	v_exp_f32_e32 v3, v3
	v_add_f32_e32 v108, v89, v109
	v_mul_f32_e32 v108, 0xbfb8aa3b, v108
	v_exp_f32_e32 v108, v108
	v_add_f32_e32 v3, 1.0, v3
	v_rcp_f32_e32 v3, v3
	v_add_f32_e32 v110, v90, v110
	v_add_f32_e32 v108, 1.0, v108
	v_mul_f32_e32 v110, 0xbfb8aa3b, v110
	v_rcp_f32_e32 v109, v108
	v_exp_f32_e32 v110, v110
	v_add_f32_e32 v111, v91, v111
	v_mul_f32_e32 v111, 0xbfb8aa3b, v111

	v_exp_f32_e32 v111, v111

	v_mul_f32_e32 v108, v244, v3

	v_add_f32_e32 v110, 1.0, v110

	v_rcp_f32_e32 v110, v110
	v_mul_f32_e32 v109, v245, v109
	v_add_f32_e32 v3, 1.0, v111
	v_rcp_f32_e32 v3, v3


	v_mul_f32_e32 v110, v246, v110


	v_mul_f32_e32 v111, v247, v3
	ds_write_b128 v2, v[108:111] offset:12352
	v_lshlrev_b32_e32 v3, 2, v0
	v_lshlrev_b32_e32 v108, 4, v0


	v_and_b32_e32 v2, 60, v3
	v_and_b32_e32 v109, 0xffffc000, v108
	v_lshlrev_b32_e32 v2, 2, v2
	v_add_u32_e32 v109, 0, v109
	v_and_b32_e32 v108, 0x3f00, v108
	v_add3_u32 v128, v109, v108, v2
	v_xor_b32_e32 v128, v200, v128
	s_waitcnt lgkmcnt(0)
	s_barrier
	ds_read_b128 v[120:123], v128 offset:25600
	ds_read_b128 v[112:115], v128 offset:58368
	v_add_u32_e32 v127, 0, v2
	v_add_u32_e32 v129, v127, v108
	ds_read_b128 v[116:119], v129
	s_waitcnt lgkmcnt(2)
	v_mul_f32_e32 v108, 0x3fb8aa3b, v120
	v_exp_f32_e32 v108, v108
	v_add_f32_e32 v109, v120, v120
	v_cmp_nlt_f32_e32 vcc, s75, v109
	s_and_saveexec_b64 s[8:9], vcc
	s_xor_b64 s[8:9], exec, s[8:9]
	v_fma_f32 v120, -v108, v108, 1.0
	s_andn2_saveexec_b64 s[8:9], s[8:9]
	v_fmamk_f32 v110, v109, 0x3c088889, v125
	v_fmaak_f32 v110, v109, v110, 0x3e2aaaab
	v_fma_f32 v110, v109, v110, 0.5
	v_fma_f32 v110, v109, v110, 1.0
	v_mul_f32_e64 v120, v110, -v109
	s_or_b64 exec, exec, s[8:9]
	v_mul_f32_e32 v109, 0x3fb8aa3b, v121
	v_exp_f32_e32 v109, v109
	v_add_f32_e32 v110, v121, v121
	v_cmp_nlt_f32_e32 vcc, s75, v110
	s_and_saveexec_b64 s[8:9], vcc
	s_xor_b64 s[8:9], exec, s[8:9]
	v_fma_f32 v121, -v109, v109, 1.0
	s_andn2_saveexec_b64 s[8:9], s[8:9]
	v_fmamk_f32 v111, v110, 0x3c088889, v125
	v_fmaak_f32 v111, v110, v111, 0x3e2aaaab
	v_fma_f32 v111, v110, v111, 0.5
	v_fma_f32 v111, v110, v111, 1.0
	v_mul_f32_e64 v121, v111, -v110
	s_or_b64 exec, exec, s[8:9]
	v_mul_f32_e32 v110, 0x3fb8aa3b, v122
	v_exp_f32_e32 v110, v110
	v_add_f32_e32 v111, v122, v122
	v_cmp_nlt_f32_e32 vcc, s75, v111
	s_and_saveexec_b64 s[8:9], vcc
	s_xor_b64 s[8:9], exec, s[8:9]
	v_fma_f32 v122, -v110, v110, 1.0
	s_andn2_saveexec_b64 s[8:9], s[8:9]
	v_fmamk_f32 v122, v111, 0x3c088889, v125
	v_fmaak_f32 v122, v111, v122, 0x3e2aaaab
	v_fma_f32 v122, v111, v122, 0.5
	v_fma_f32 v122, v111, v122, 1.0
	v_mul_f32_e64 v122, v122, -v111
	s_or_b64 exec, exec, s[8:9]
	v_mul_f32_e32 v111, 0x3fb8aa3b, v123
	v_exp_f32_e32 v111, v111
	v_add_f32_e32 v130, v123, v123
	v_cmp_nlt_f32_e32 vcc, s75, v130
	s_and_saveexec_b64 s[8:9], vcc
	s_xor_b64 s[8:9], exec, s[8:9]
	v_fma_f32 v123, -v111, v111, 1.0
	s_andn2_saveexec_b64 s[8:9], s[8:9]
	v_fmamk_f32 v123, v130, 0x3c088889, v125
	v_fmaak_f32 v123, v130, v123, 0x3e2aaaab
	v_fma_f32 v123, v130, v123, 0.5
	v_fma_f32 v123, v130, v123, 1.0
	v_mul_f32_e64 v123, v123, -v130
	s_or_b64 exec, exec, s[8:9]
	v_max_f32_e32 v120, v120, v120
	v_max_f32_e32 v120, 0, v120
	v_sqrt_f32_e32 v120, v120
	v_max_f32_e32 v121, v121, v121
	v_max_f32_e32 v121, 0, v121
	v_sqrt_f32_e32 v121, v121
	s_waitcnt lgkmcnt(1)
	v_mul_f32_e32 v112, v112, v120
	s_waitcnt lgkmcnt(0)
	v_mul_f32_e32 v112, v116, v112
	v_max_f32_e32 v116, v122, v122
	v_max_f32_e32 v120, v123, v123
	v_max_f32_e32 v116, 0, v116
	v_max_f32_e32 v120, 0, v120
	v_sqrt_f32_e32 v116, v116
	v_sqrt_f32_e32 v120, v120
	v_mul_f32_e32 v113, v113, v121
	v_mul_f32_e32 v113, v117, v113
	v_mul_f32_e32 v114, v114, v116
	v_mul_f32_e32 v115, v115, v120
	v_mul_f32_e32 v114, v118, v114
	v_mul_f32_e32 v115, v119, v115
	ds_write_b128 v128, v[108:111] offset:25600
	ds_write_b128 v128, v[112:115] offset:58368
	v_add_u32_e32 v108, 0x800, v3
	v_and_b32_e32 v109, 0x3ffff000, v108
	v_and_b32_e32 v108, 0xfc0, v108
	v_lshl_add_u32 v109, v109, 2, 0
	v_lshlrev_b32_e32 v108, 2, v108
	v_add3_u32 v130, v109, v108, v2
	v_xor_b32_e32 v130, v200, v130
	ds_read_b128 v[120:123], v130 offset:25600
	ds_read_b128 v[112:115], v130 offset:58368
	v_add_u32_e32 v108, v127, v108
	ds_read_b128 v[116:119], v108
	s_waitcnt lgkmcnt(2)
	v_mul_f32_e32 v108, 0x3fb8aa3b, v120
	v_exp_f32_e32 v108, v108
	v_add_f32_e32 v109, v120, v120
	v_cmp_nlt_f32_e32 vcc, s75, v109
	s_and_saveexec_b64 s[8:9], vcc
	s_xor_b64 s[8:9], exec, s[8:9]
	v_fma_f32 v120, -v108, v108, 1.0
	s_andn2_saveexec_b64 s[8:9], s[8:9]
	v_fmamk_f32 v110, v109, 0x3c088889, v125
	v_fmaak_f32 v110, v109, v110, 0x3e2aaaab
	v_fma_f32 v110, v109, v110, 0.5
	v_fma_f32 v110, v109, v110, 1.0
	v_mul_f32_e64 v120, v110, -v109
	s_or_b64 exec, exec, s[8:9]
	v_mul_f32_e32 v109, 0x3fb8aa3b, v121
	v_exp_f32_e32 v109, v109
	v_add_f32_e32 v110, v121, v121
	v_cmp_nlt_f32_e32 vcc, s75, v110
	s_and_saveexec_b64 s[8:9], vcc
	s_xor_b64 s[8:9], exec, s[8:9]
	v_fma_f32 v121, -v109, v109, 1.0
	s_andn2_saveexec_b64 s[8:9], s[8:9]
	v_fmamk_f32 v111, v110, 0x3c088889, v125
	v_fmaak_f32 v111, v110, v111, 0x3e2aaaab
	v_fma_f32 v111, v110, v111, 0.5
	v_fma_f32 v111, v110, v111, 1.0
	v_mul_f32_e64 v121, v111, -v110
	s_or_b64 exec, exec, s[8:9]
	v_mul_f32_e32 v110, 0x3fb8aa3b, v122
	v_exp_f32_e32 v110, v110
	v_add_f32_e32 v111, v122, v122
	v_cmp_nlt_f32_e32 vcc, s75, v111
	s_and_saveexec_b64 s[8:9], vcc
	s_xor_b64 s[8:9], exec, s[8:9]
	v_fma_f32 v122, -v110, v110, 1.0
	s_andn2_saveexec_b64 s[8:9], s[8:9]
	v_fmamk_f32 v122, v111, 0x3c088889, v125
	v_fmaak_f32 v122, v111, v122, 0x3e2aaaab
	v_fma_f32 v122, v111, v122, 0.5
	v_fma_f32 v122, v111, v122, 1.0
	v_mul_f32_e64 v122, v122, -v111
	s_or_b64 exec, exec, s[8:9]
	v_mul_f32_e32 v111, 0x3fb8aa3b, v123
	v_exp_f32_e32 v111, v111
	v_add_f32_e32 v131, v123, v123
	v_cmp_nlt_f32_e32 vcc, s75, v131
	s_and_saveexec_b64 s[8:9], vcc
	s_xor_b64 s[8:9], exec, s[8:9]
	v_fma_f32 v123, -v111, v111, 1.0
	s_andn2_saveexec_b64 s[8:9], s[8:9]
	v_fmamk_f32 v123, v131, 0x3c088889, v125
	v_fmaak_f32 v123, v131, v123, 0x3e2aaaab
	v_fma_f32 v123, v131, v123, 0.5
	v_fma_f32 v123, v131, v123, 1.0
	v_mul_f32_e64 v123, v123, -v131
	s_or_b64 exec, exec, s[8:9]
	v_max_f32_e32 v120, v120, v120
	v_max_f32_e32 v120, 0, v120
	v_sqrt_f32_e32 v120, v120
	v_max_f32_e32 v121, v121, v121
	v_max_f32_e32 v121, 0, v121
	v_sqrt_f32_e32 v121, v121
	s_waitcnt lgkmcnt(1)
	v_mul_f32_e32 v112, v112, v120
	s_waitcnt lgkmcnt(0)
	v_mul_f32_e32 v112, v116, v112
	v_max_f32_e32 v116, v122, v122
	v_max_f32_e32 v120, v123, v123
	v_max_f32_e32 v116, 0, v116
	v_max_f32_e32 v120, 0, v120
	v_sqrt_f32_e32 v116, v116
	v_sqrt_f32_e32 v120, v120
	v_mul_f32_e32 v113, v113, v121
	v_mul_f32_e32 v113, v117, v113
	v_mul_f32_e32 v114, v114, v116
	v_mul_f32_e32 v115, v115, v120
	v_mul_f32_e32 v114, v118, v114
	v_mul_f32_e32 v115, v119, v115
	ds_write_b128 v130, v[108:111] offset:25600
	ds_write_b128 v130, v[112:115] offset:58368
	ds_read_b128 v[120:123], v128 offset:41984
	v_add_u32_e32 v130, 0xe400, v128
	ds_read_b128 v[112:115], v130 offset:16384
	ds_read_b128 v[116:119], v129
	s_waitcnt lgkmcnt(2)
	v_mul_f32_e32 v108, 0x3fb8aa3b, v120
	v_exp_f32_e32 v108, v108
	v_add_f32_e32 v109, v120, v120
	v_cmp_nlt_f32_e32 vcc, s75, v109
	s_and_saveexec_b64 s[8:9], vcc
	s_xor_b64 s[8:9], exec, s[8:9]
	v_fma_f32 v120, -v108, v108, 1.0
	s_andn2_saveexec_b64 s[8:9], s[8:9]
	v_fmamk_f32 v110, v109, 0x3c088889, v125
	v_fmaak_f32 v110, v109, v110, 0x3e2aaaab
	v_fma_f32 v110, v109, v110, 0.5
	v_fma_f32 v110, v109, v110, 1.0
	v_mul_f32_e64 v120, v110, -v109
	s_or_b64 exec, exec, s[8:9]
	v_mul_f32_e32 v109, 0x3fb8aa3b, v121
	v_exp_f32_e32 v109, v109
	v_add_f32_e32 v110, v121, v121
	v_cmp_nlt_f32_e32 vcc, s75, v110
	s_and_saveexec_b64 s[8:9], vcc
	s_xor_b64 s[8:9], exec, s[8:9]
	v_fma_f32 v121, -v109, v109, 1.0
	s_andn2_saveexec_b64 s[8:9], s[8:9]
	v_fmamk_f32 v111, v110, 0x3c088889, v125
	v_fmaak_f32 v111, v110, v111, 0x3e2aaaab
	v_fma_f32 v111, v110, v111, 0.5
	v_fma_f32 v111, v110, v111, 1.0
	v_mul_f32_e64 v121, v111, -v110
	s_or_b64 exec, exec, s[8:9]
	v_mul_f32_e32 v110, 0x3fb8aa3b, v122
	v_exp_f32_e32 v110, v110
	v_add_f32_e32 v111, v122, v122
	v_cmp_nlt_f32_e32 vcc, s75, v111
	s_and_saveexec_b64 s[8:9], vcc
	s_xor_b64 s[8:9], exec, s[8:9]
	v_fma_f32 v122, -v110, v110, 1.0
	s_andn2_saveexec_b64 s[8:9], s[8:9]
	v_fmamk_f32 v122, v111, 0x3c088889, v125
	v_fmaak_f32 v122, v111, v122, 0x3e2aaaab
	v_fma_f32 v122, v111, v122, 0.5
	v_fma_f32 v122, v111, v122, 1.0
	v_mul_f32_e64 v122, v122, -v111
	s_or_b64 exec, exec, s[8:9]
	v_mul_f32_e32 v111, 0x3fb8aa3b, v123
	v_exp_f32_e32 v111, v111
	v_add_f32_e32 v129, v123, v123
	v_cmp_nlt_f32_e32 vcc, s75, v129
	s_and_saveexec_b64 s[8:9], vcc
	s_xor_b64 s[8:9], exec, s[8:9]
	v_fma_f32 v123, -v111, v111, 1.0
	s_andn2_saveexec_b64 s[8:9], s[8:9]
	v_fmamk_f32 v123, v129, 0x3c088889, v125
	v_fmaak_f32 v123, v129, v123, 0x3e2aaaab
	v_fma_f32 v123, v129, v123, 0.5
	v_fma_f32 v123, v129, v123, 1.0
	v_mul_f32_e64 v123, v123, -v129
	s_or_b64 exec, exec, s[8:9]
	v_max_f32_e32 v120, v120, v120
	v_max_f32_e32 v120, 0, v120
	v_sqrt_f32_e32 v120, v120
	v_max_f32_e32 v121, v121, v121
	v_max_f32_e32 v121, 0, v121
	v_sqrt_f32_e32 v121, v121
	s_waitcnt lgkmcnt(1)
	v_mul_f32_e32 v112, v112, v120
	s_waitcnt lgkmcnt(0)
	v_mul_f32_e32 v112, v116, v112
	v_max_f32_e32 v116, v122, v122
	v_max_f32_e32 v120, v123, v123
	v_max_f32_e32 v116, 0, v116
	v_max_f32_e32 v120, 0, v120
	v_sqrt_f32_e32 v116, v116
	v_sqrt_f32_e32 v120, v120
	v_mul_f32_e32 v113, v113, v121
	v_add_u32_e32 v3, 0x1800, v3
	v_mul_f32_e32 v114, v114, v116
	v_mul_f32_e32 v115, v115, v120
	v_mul_f32_e32 v113, v117, v113
	v_mul_f32_e32 v114, v118, v114
	v_mul_f32_e32 v115, v119, v115
	ds_write_b128 v128, v[108:111] offset:41984
	ds_write_b128 v130, v[112:115] offset:16384
	v_and_b32_e32 v108, 0x3ffff000, v3
	v_and_b32_e32 v3, 0xfc0, v3
	v_lshl_add_u32 v108, v108, 2, 0
	v_lshlrev_b32_e32 v3, 2, v3
	v_add3_u32 v2, v108, v3, v2
	v_xor_b32_e32 v2, v200, v2
	ds_read_b128 v[120:123], v2 offset:25600
	ds_read_b128 v[112:115], v2 offset:58368
	v_add_u32_e32 v3, v127, v3
	ds_read_b128 v[116:119], v3
	s_waitcnt lgkmcnt(2)
	v_mul_f32_e32 v3, 0x3fb8aa3b, v120
	v_exp_f32_e32 v108, v3
	v_add_f32_e32 v109, v120, v120
	v_cmp_nlt_f32_e32 vcc, s75, v109
	s_and_saveexec_b64 s[8:9], vcc
	s_xor_b64 s[8:9], exec, s[8:9]
	v_fma_f32 v3, -v108, v108, 1.0
	s_andn2_saveexec_b64 s[8:9], s[8:9]
	v_fmamk_f32 v3, v109, 0x3c088889, v125
	v_fmaak_f32 v3, v109, v3, 0x3e2aaaab
	v_fma_f32 v3, v109, v3, 0.5
	v_fma_f32 v3, v109, v3, 1.0
	v_mul_f32_e64 v3, v3, -v109
	s_or_b64 exec, exec, s[8:9]
	v_mul_f32_e32 v109, 0x3fb8aa3b, v121
	v_exp_f32_e32 v109, v109
	v_add_f32_e32 v110, v121, v121
	v_cmp_nlt_f32_e32 vcc, s75, v110
	s_and_saveexec_b64 s[8:9], vcc
	s_xor_b64 s[8:9], exec, s[8:9]
	v_fma_f32 v121, -v109, v109, 1.0
	s_andn2_saveexec_b64 s[8:9], s[8:9]
	v_fmamk_f32 v111, v110, 0x3c088889, v125
	v_fmaak_f32 v111, v110, v111, 0x3e2aaaab
	v_fma_f32 v111, v110, v111, 0.5
	v_fma_f32 v111, v110, v111, 1.0
	v_mul_f32_e64 v121, v111, -v110
	s_or_b64 exec, exec, s[8:9]
	v_mul_f32_e32 v110, 0x3fb8aa3b, v122
	v_exp_f32_e32 v110, v110
	v_add_f32_e32 v111, v122, v122
	v_cmp_nlt_f32_e32 vcc, s75, v111
	s_and_saveexec_b64 s[8:9], vcc
	s_xor_b64 s[8:9], exec, s[8:9]
	v_fma_f32 v122, -v110, v110, 1.0
	s_andn2_saveexec_b64 s[8:9], s[8:9]
	v_fmamk_f32 v120, v111, 0x3c088889, v125
	v_fmaak_f32 v120, v111, v120, 0x3e2aaaab
	v_fma_f32 v120, v111, v120, 0.5
	v_fma_f32 v120, v111, v120, 1.0
	v_mul_f32_e64 v122, v120, -v111
	s_or_b64 exec, exec, s[8:9]
	v_mul_f32_e32 v111, 0x3fb8aa3b, v123
	v_exp_f32_e32 v111, v111
	v_add_f32_e32 v120, v123, v123
	v_cmp_nlt_f32_e32 vcc, s75, v120
	s_and_saveexec_b64 s[8:9], vcc
	s_xor_b64 s[8:9], exec, s[8:9]
	v_fma_f32 v123, -v111, v111, 1.0
	s_andn2_saveexec_b64 s[8:9], s[8:9]
	v_fmamk_f32 v123, v120, 0x3c088889, v125
	v_fmaak_f32 v123, v120, v123, 0x3e2aaaab
	v_fma_f32 v123, v120, v123, 0.5
	v_fma_f32 v123, v120, v123, 1.0
	v_mul_f32_e64 v123, v123, -v120
	s_or_b64 exec, exec, s[8:9]
	v_max_f32_e32 v3, v3, v3
	v_max_f32_e32 v3, 0, v3
	v_sqrt_f32_e32 v3, v3
	v_max_f32_e32 v121, v121, v121
	v_max_f32_e32 v121, 0, v121
	v_mov_b32_e32 v120, 0
	s_waitcnt lgkmcnt(1)
	v_mul_f32_e32 v3, v112, v3
	v_sqrt_f32_e32 v112, v121
	v_max_f32_e32 v121, v122, v122
	v_max_f32_e32 v121, 0, v121
	v_sqrt_f32_e32 v121, v121
	s_waitcnt lgkmcnt(0)
	v_mul_f32_e32 v116, v116, v3
	v_mul_f32_e32 v3, v113, v112
	v_mul_f32_e32 v117, v117, v3
	v_mul_f32_e32 v3, v114, v121
	v_mul_f32_e32 v118, v118, v3
	v_max_f32_e32 v3, v123, v123
	v_max_f32_e32 v3, 0, v3
	v_sqrt_f32_e32 v3, v3
	v_ashrrev_i32_e32 v114, 7, v0
	v_and_b32_e32 v121, 0x7f, v0
	v_bfe_u32 v113, v0, 6, 1
	v_mul_f32_e32 v3, v115, v3
	v_mul_f32_e32 v119, v119, v3
	ds_write_b128 v2, v[108:111] offset:25600
	ds_write_b128 v2, v[116:119] offset:58368
	v_lshlrev_b32_e32 v2, 4, v114

	v_and_b32_e32 v112, 63, v0


	s_waitcnt lgkmcnt(0)
	s_barrier
	ds_read2st64_b32 v[116:117], v172 offset0:100 offset1:228


	ds_read2st64_b32 v[118:119], v173 offset0:100 offset1:228


	ds_read2st64_b32 v[122:123], v174 offset0:100 offset1:228


	ds_read2st64_b32 v[128:129], v175 offset0:100 offset1:228


	ds_read2st64_b32 v[130:131], v176 offset0:100 offset1:228


	ds_read2st64_b32 v[132:133], v177 offset0:100 offset1:228


	ds_read2st64_b32 v[134:135], v178 offset0:100 offset1:228


	ds_read2st64_b32 v[136:137], v179 offset0:100 offset1:228


	ds_read2st64_b32 v[138:139], v180 offset0:100 offset1:228


	ds_read2st64_b32 v[140:141], v181 offset0:100 offset1:228


	ds_read2st64_b32 v[108:109], v170 offset0:100 offset1:228


	ds_read2st64_b32 v[110:111], v171 offset0:100 offset1:228
	ds_read2st64_b32 v[142:143], v182 offset0:100 offset1:228


	s_waitcnt lgkmcnt(2)
	v_fma_f32 v109, 0, v108, v109
	ds_read2st64_b32 v[144:145], v183 offset0:100 offset1:228
	v_or_b32_e32 v115, 14, v2
	s_waitcnt lgkmcnt(2)
	v_mul_f32_e32 v108, v108, v110
	v_fmac_f32_e32 v111, v109, v110
	v_sub_u32_e32 v127, 63, v115
	v_mul_f32_e32 v108, v108, v116
	v_fmac_f32_e32 v117, v111, v116

	v_mul_f32_e32 v108, v108, v118
	v_fmac_f32_e32 v119, v117, v118

	v_mul_f32_e32 v108, v108, v122
	v_fmac_f32_e32 v123, v119, v122

	v_or_b32_e32 v2, 15, v2
	v_mul_f32_e32 v108, v108, v128
	v_fmac_f32_e32 v129, v123, v128
	ds_read2st64_b32 v[146:147], v184 offset0:100 offset1:228
	v_sub_u32_e32 v115, 63, v2
	v_mul_f32_e32 v108, v108, v130
	v_fmac_f32_e32 v131, v129, v130

	v_mul_f32_e32 v108, v108, v132
	v_fmac_f32_e32 v133, v131, v132

	v_mul_f32_e32 v108, v108, v134
	v_fmac_f32_e32 v135, v133, v134

	v_mul_f32_e32 v108, v108, v136
	v_fmac_f32_e32 v137, v135, v136
	ds_read2st64_b32 v[2:3], v185 offset0:100 offset1:228
	v_mul_f32_e32 v108, v108, v138
	v_fmac_f32_e32 v139, v137, v138
	v_mul_f32_e32 v108, v108, v140
	v_fmac_f32_e32 v141, v139, v140
	s_waitcnt lgkmcnt(3)
	v_mul_f32_e32 v108, v108, v142
	v_fmac_f32_e32 v143, v141, v142
	s_waitcnt lgkmcnt(2)
	v_mul_f32_e32 v108, v108, v144
	v_fmac_f32_e32 v145, v143, v144
	s_waitcnt lgkmcnt(1)
	v_mul_f32_e32 v108, v108, v146
	v_fmac_f32_e32 v147, v145, v146
	v_lshl_add_u32 v0, v0, 2, 0
	s_waitcnt lgkmcnt(0)
	v_mul_f32_e32 v108, v108, v2
	v_fmac_f32_e32 v3, v147, v2
	v_add_u32_e32 v2, 0x16400, v0
	v_add_u32_e32 v0, 0x16c00, v0
	ds_write_b32 v2, v108
	ds_write_b32 v0, v3
	v_cmp_lt_i32_e32 vcc, 0, v114
	v_mov_b32_e32 v0, 1.0
	v_lshl_add_u32 v2, v121, 2, 0
	s_waitcnt vmcnt(0) lgkmcnt(0)
	s_barrier
	s_and_saveexec_b64 s[8:9], vcc
	s_cbranch_execnz .LBB0_431
	s_or_b64 exec, exec, s[8:9]
	v_cmp_lt_i32_e32 vcc, 1, v114
	s_and_saveexec_b64 s[8:9], vcc
	s_cbranch_execnz .LBB0_432

.LBB0_363:
	v_mov_b32_e32 v0, v204
	v_and_b32_e32 v3, 0xffff0000, v68
	v_lshlrev_b32_e32 v2, 3, v0
	v_and_b32_e32 v116, 56, v2
	v_lshlrev_b32_e32 v2, 16, v68
	s_nop 0
	v_pk_fma_f32 v[2:3], v[32:33], v[2:3], v[48:49]
	v_lshlrev_b32_e32 v108, 16, v72
	v_and_b32_e32 v109, 0xffff0000, v72
	v_pk_fma_f32 v[2:3], v[8:9], v[108:109], v[2:3]
	v_lshlrev_b32_e32 v108, 16, v100
	v_and_b32_e32 v109, 0xffff0000, v100
	v_pk_fma_f32 v[2:3], v[12:13], v[108:109], v[2:3]
	v_lshlrev_b32_e32 v108, 16, v104
	v_and_b32_e32 v109, 0xffff0000, v104
	v_pk_fma_f32 v[108:109], v[16:17], v[108:109], v[2:3]
	v_lshlrev_b32_e32 v2, 16, v70
	v_and_b32_e32 v3, 0xffff0000, v70
	v_pk_fma_f32 v[2:3], v[28:29], v[2:3], v[44:45]
	v_lshlrev_b32_e32 v110, 16, v74
	v_and_b32_e32 v111, 0xffff0000, v74
	v_pk_fma_f32 v[2:3], v[4:5], v[110:111], v[2:3]
	v_lshlrev_b32_e32 v110, 16, v102
	v_and_b32_e32 v111, 0xffff0000, v102
	v_pk_fma_f32 v[2:3], v[20:21], v[110:111], v[2:3]
	v_lshlrev_b32_e32 v110, 16, v106
	v_and_b32_e32 v111, 0xffff0000, v106
	v_pk_fma_f32 v[112:113], v[36:37], v[110:111], v[2:3]
	v_lshlrev_b32_e32 v2, 16, v69
	v_and_b32_e32 v3, 0xffff0000, v69
	v_pk_fma_f32 v[2:3], v[34:35], v[2:3], v[50:51]
	v_lshlrev_b32_e32 v110, 16, v73
	v_and_b32_e32 v111, 0xffff0000, v73
	v_pk_fma_f32 v[2:3], v[10:11], v[110:111], v[2:3]
	v_lshlrev_b32_e32 v110, 16, v101
	v_and_b32_e32 v111, 0xffff0000, v101
	v_pk_fma_f32 v[2:3], v[14:15], v[110:111], v[2:3]
	v_lshlrev_b32_e32 v110, 16, v105
	v_and_b32_e32 v111, 0xffff0000, v105
	v_pk_fma_f32 v[110:111], v[18:19], v[110:111], v[2:3]
	v_lshlrev_b32_e32 v2, 16, v71
	v_and_b32_e32 v3, 0xffff0000, v71
	v_pk_fma_f32 v[2:3], v[30:31], v[2:3], v[46:47]
	v_lshlrev_b32_e32 v114, 16, v75
	v_and_b32_e32 v115, 0xffff0000, v75
	v_pk_fma_f32 v[2:3], v[6:7], v[114:115], v[2:3]
	v_lshlrev_b32_e32 v114, 16, v103
	v_and_b32_e32 v115, 0xffff0000, v103
	v_pk_fma_f32 v[2:3], v[22:23], v[114:115], v[2:3]
	v_lshlrev_b32_e32 v114, 16, v107
	v_and_b32_e32 v115, 0xffff0000, v107
	v_pk_fma_f32 v[114:115], v[38:39], v[114:115], v[2:3]
	v_ashrrev_i32_e32 v3, 3, v0
	v_lshl_add_u32 v117, v3, 8, 0
	v_lshl_add_u32 v118, v116, 2, v117
	ds_write_b128 v118, v[108:111]
	ds_write_b128 v118, v[112:115] offset:16
	v_cvt_pk_bf16_f32 v108, v108, v109
	v_cvt_pk_bf16_f32 v109, v110, v111
	v_cvt_pk_bf16_f32 v110, v112, v113
	v_mul_lo_u32 v3, v3, s67
	v_lshlrev_b32_e32 v112, 1, v116
	v_and_b32_e32 v127, 15, v0
	v_cvt_pk_bf16_f32 v111, v114, v115
	v_add3_u32 v3, v117, v3, v112
	v_and_b32_e32 v2, 48, v0
	ds_write_b128 v3, v[108:111] offset:16384
	v_mul_u32_u24_e32 v3, 0x90, v127
	v_add3_u32 v3, 0, v2, v3
	s_waitcnt lgkmcnt(0)
	s_barrier
	ds_read_b128 v[108:111], v3 offset:16384
	ds_read_b128 v[112:115], v3 offset:16448
	ds_read_b128 v[120:123], v3 offset:18688
	ds_read_b128 v[128:131], v3 offset:18752
	ds_read_b128 v[136:139], v3 offset:20992
	ds_read_b128 v[140:143], v3 offset:21056
	s_waitcnt lgkmcnt(5)
	v_mfma_f32_16x16x32_bf16 v[116:119], v[60:63], v[108:111], 0
	ds_read_b128 v[148:151], v3 offset:23296
	ds_read_b128 v[154:157], v3 offset:23360
	v_mov_b32_e32 v3, s2
	v_cmp_gt_u32_e32 vcc, s45, v0
	s_nop 0
	v_mfma_f32_16x16x32_bf16 v[108:111], v[76:79], v[108:111], 0
	v_lshlrev_b32_e32 v127, 8, v127
	s_waitcnt lgkmcnt(3)
	v_mfma_f32_16x16x32_bf16 v[144:147], v[60:63], v[136:139], 0
	v_mfma_f32_16x16x32_bf16 v[136:139], v[76:79], v[136:139], 0
	v_mfma_f32_16x16x32_bf16 v[162:165], v[64:67], v[112:115], v[116:119]
	s_nop 0
	v_mfma_f32_16x16x32_bf16 v[166:169], v[80:83], v[112:115], v[108:111]
	s_waitcnt lgkmcnt(2)
	v_mfma_f32_16x16x32_bf16 v[112:115], v[80:83], v[140:143], v[136:139]
	s_nop 2
	v_mov_b32_e32 v136, s73
	v_cndmask_b32_e32 v3, v3, v136, vcc
	v_lshlrev_b32_e32 v136, 7, v0
	v_and_b32_e32 v136, 0x4000, v136
	v_add3_u32 v3, v3, v136, v127
	s_nop 0
	v_add_f32_e32 v136, v84, v162
	v_mul_f32_e32 v136, 0xbfb8aa3b, v136
	v_add_f32_e32 v137, v85, v163
	v_exp_f32_e32 v136, v136
	v_mul_f32_e32 v137, 0xbfb8aa3b, v137
	v_exp_f32_e32 v137, v137
	v_lshlrev_b32_e32 v127, 1, v0
	v_and_b32_e32 v127, 0x80, v127
	v_add_f32_e32 v136, 1.0, v136
	v_rcp_f32_e32 v136, v136
	v_add3_u32 v2, v3, v127, v2
	v_xor_b32_e32 v2, v201, v2
	v_add_f32_e32 v3, 1.0, v137
	v_add_f32_e32 v137, v86, v164
	v_mul_f32_e32 v137, 0xbfb8aa3b, v137
	v_rcp_f32_e32 v3, v3
	v_exp_f32_e32 v137, v137
	v_add_f32_e32 v138, v87, v165
	v_mul_f32_e32 v138, 0xbfb8aa3b, v138

	v_exp_f32_e32 v138, v138
	s_nop 0

	v_mul_f32_e32 v136, v240, v136

	v_add_f32_e32 v137, 1.0, v137
	v_mfma_f32_16x16x32_bf16 v[132:135], v[60:63], v[120:123], 0

	v_rcp_f32_e32 v139, v137
	v_mul_f32_e32 v137, v241, v3
	v_add_f32_e32 v3, 1.0, v138
	v_rcp_f32_e32 v3, v3
	s_nop 0
	v_mfma_f32_16x16x32_bf16 v[132:135], v[64:67], v[128:131], v[132:135]


	v_mul_f32_e32 v138, v242, v139


	v_mul_f32_e32 v139, v243, v3
	s_nop 1
	s_nop 3
	v_add_f32_e32 v3, v84, v132
	v_mul_f32_e32 v3, 0xbfb8aa3b, v3
	v_exp_f32_e32 v3, v3
	v_add_f32_e32 v127, v85, v133
	v_mul_f32_e32 v127, 0xbfb8aa3b, v127
	v_exp_f32_e32 v127, v127
	v_add_f32_e32 v3, 1.0, v3
	v_rcp_f32_e32 v3, v3
	v_add_f32_e32 v133, v86, v134
	v_add_f32_e32 v127, 1.0, v127
	v_mul_f32_e32 v133, 0xbfb8aa3b, v133
	v_rcp_f32_e32 v127, v127
	v_exp_f32_e32 v133, v133
	v_add_f32_e32 v134, v87, v135
	v_mul_f32_e32 v134, 0xbfb8aa3b, v134

	v_exp_f32_e32 v134, v134

	v_mul_f32_e32 v132, v240, v3

	v_add_f32_e32 v133, 1.0, v133
	v_mfma_f32_16x16x32_bf16 v[120:123], v[76:79], v[120:123], 0

	v_rcp_f32_e32 v135, v133
	v_mul_f32_e32 v133, v241, v127
	v_add_f32_e32 v3, 1.0, v134
	v_rcp_f32_e32 v3, v3
	s_nop 0
	v_mfma_f32_16x16x32_bf16 v[116:119], v[80:83], v[128:131], v[120:123]


	v_mul_f32_e32 v134, v242, v135
	v_mfma_f32_16x16x32_bf16 v[120:123], v[64:67], v[140:143], v[144:147]


	v_mul_f32_e32 v135, v243, v3
	s_waitcnt lgkmcnt(1)
	v_mfma_f32_16x16x32_bf16 v[158:161], v[60:63], v[148:151], 0
	s_nop 3
	v_add_f32_e32 v118, v90, v118
	s_nop 1
	s_nop 1
	v_add_f32_e32 v3, v84, v120
	v_mul_f32_e32 v3, 0xbfb8aa3b, v3
	v_exp_f32_e32 v3, v3
	v_add_f32_e32 v120, v85, v121
	v_mul_f32_e32 v120, 0xbfb8aa3b, v120
	v_exp_f32_e32 v120, v120
	v_add_f32_e32 v3, 1.0, v3
	v_rcp_f32_e32 v3, v3
	v_add_f32_e32 v122, v86, v122
	v_add_f32_e32 v120, 1.0, v120
	v_mul_f32_e32 v122, 0xbfb8aa3b, v122
	v_rcp_f32_e32 v121, v120
	v_exp_f32_e32 v122, v122
	v_add_f32_e32 v123, v87, v123
	v_mul_f32_e32 v123, 0xbfb8aa3b, v123

	v_exp_f32_e32 v123, v123

	v_mul_f32_e32 v120, v240, v3

	v_add_f32_e32 v122, 1.0, v122

	v_rcp_f32_e32 v122, v122
	v_mul_f32_e32 v121, v241, v121
	v_add_f32_e32 v3, 1.0, v123
	v_rcp_f32_e32 v3, v3
	s_waitcnt lgkmcnt(0)
	v_mfma_f32_16x16x32_bf16 v[128:131], v[64:67], v[154:157], v[158:161]
	ds_write_b128 v2, v[136:139]
	ds_write_b128 v2, v[132:135] offset:4096


	v_mul_f32_e32 v122, v242, v122


	v_mul_f32_e32 v123, v243, v3
	s_nop 1
	s_nop 3
	v_add_f32_e32 v3, v84, v128
	v_mul_f32_e32 v3, 0xbfb8aa3b, v3
	v_exp_f32_e32 v3, v3
	v_add_f32_e32 v127, v85, v129
	v_mul_f32_e32 v127, 0xbfb8aa3b, v127
	v_exp_f32_e32 v127, v127
	v_add_f32_e32 v3, 1.0, v3
	v_rcp_f32_e32 v3, v3
	ds_write_b128 v2, v[120:123] offset:8192
	v_add_f32_e32 v122, v86, v130
	v_add_f32_e32 v120, 1.0, v127
	v_mul_f32_e32 v122, 0xbfb8aa3b, v122
	v_rcp_f32_e32 v121, v120
	v_exp_f32_e32 v122, v122
	v_add_f32_e32 v123, v87, v131
	v_mul_f32_e32 v123, 0xbfb8aa3b, v123

	v_exp_f32_e32 v123, v123

	v_mul_f32_e32 v120, v240, v3

	v_add_f32_e32 v122, 1.0, v122

	v_rcp_f32_e32 v122, v122
	v_mul_f32_e32 v121, v241, v121
	v_add_f32_e32 v3, 1.0, v123
	v_rcp_f32_e32 v3, v3


	v_mul_f32_e32 v122, v242, v122


	v_mul_f32_e32 v123, v243, v3
	v_add_f32_e32 v3, v88, v166
	v_mul_f32_e32 v3, 0xbfb8aa3b, v3
	v_exp_f32_e32 v3, v3
	v_add_f32_e32 v127, v89, v167
	v_mul_f32_e32 v127, 0xbfb8aa3b, v127
	v_exp_f32_e32 v127, v127
	v_add_f32_e32 v3, 1.0, v3
	v_rcp_f32_e32 v3, v3
	ds_write_b128 v2, v[120:123] offset:12288
	v_add_f32_e32 v122, v90, v168
	v_add_f32_e32 v120, 1.0, v127
	v_mul_f32_e32 v122, 0xbfb8aa3b, v122
	v_rcp_f32_e32 v121, v120
	v_exp_f32_e32 v122, v122
	v_add_f32_e32 v123, v91, v169
	v_mul_f32_e32 v123, 0xbfb8aa3b, v123

	v_exp_f32_e32 v123, v123
	s_nop 0

	v_mul_f32_e32 v120, v244, v3

	v_add_f32_e32 v122, 1.0, v122

	v_rcp_f32_e32 v122, v122
	v_mul_f32_e32 v121, v245, v121
	v_add_f32_e32 v3, 1.0, v123
	v_rcp_f32_e32 v3, v3


	v_mul_f32_e32 v122, v246, v122


	v_mul_f32_e32 v123, v247, v3
	v_add_f32_e32 v3, v88, v116
	ds_write_b128 v2, v[120:123] offset:64
	v_mul_f32_e32 v3, 0xbfb8aa3b, v3
	v_exp_f32_e32 v3, v3
	v_add_f32_e32 v116, v89, v117
	v_mul_f32_e32 v116, 0xbfb8aa3b, v116
	v_exp_f32_e32 v116, v116
	v_add_f32_e32 v3, 1.0, v3
	v_rcp_f32_e32 v3, v3
	v_mul_f32_e32 v118, 0xbfb8aa3b, v118
	v_add_f32_e32 v116, 1.0, v116
	v_rcp_f32_e32 v117, v116
	v_exp_f32_e32 v118, v118
	v_add_f32_e32 v119, v91, v119
	v_mul_f32_e32 v119, 0xbfb8aa3b, v119

	v_exp_f32_e32 v119, v119

	v_mul_f32_e32 v116, v244, v3

	v_add_f32_e32 v118, 1.0, v118

	v_rcp_f32_e32 v118, v118
	v_mul_f32_e32 v117, v245, v117
	v_add_f32_e32 v3, 1.0, v119
	v_rcp_f32_e32 v3, v3


	v_mul_f32_e32 v118, v246, v118


	v_mul_f32_e32 v119, v247, v3
	v_add_f32_e32 v3, v88, v112
	ds_write_b128 v2, v[116:119] offset:4160
	v_mul_f32_e32 v3, 0xbfb8aa3b, v3
	v_exp_f32_e32 v3, v3
	v_add_f32_e32 v112, v89, v113
	v_mul_f32_e32 v112, 0xbfb8aa3b, v112
	v_exp_f32_e32 v112, v112
	v_add_f32_e32 v3, 1.0, v3
	v_rcp_f32_e32 v3, v3
	v_add_f32_e32 v114, v90, v114
	v_add_f32_e32 v112, 1.0, v112
	v_mul_f32_e32 v114, 0xbfb8aa3b, v114
	v_rcp_f32_e32 v113, v112
	v_exp_f32_e32 v114, v114
	v_add_f32_e32 v115, v91, v115
	v_mul_f32_e32 v115, 0xbfb8aa3b, v115

	v_exp_f32_e32 v115, v115

	v_mul_f32_e32 v112, v244, v3

	v_add_f32_e32 v114, 1.0, v114
	v_mfma_f32_16x16x32_bf16 v[148:151], v[76:79], v[148:151], 0

	v_rcp_f32_e32 v114, v114
	v_mul_f32_e32 v113, v245, v113
	v_add_f32_e32 v3, 1.0, v115
	v_rcp_f32_e32 v3, v3
	s_nop 0
	v_mfma_f32_16x16x32_bf16 v[108:111], v[80:83], v[154:157], v[148:151]


	v_mul_f32_e32 v114, v246, v114


	v_mul_f32_e32 v115, v247, v3
	s_nop 1
	ds_write_b128 v2, v[112:115] offset:8256
	s_nop 3
	v_add_f32_e32 v3, v88, v108
	v_mul_f32_e32 v3, 0xbfb8aa3b, v3
	v_exp_f32_e32 v3, v3
	v_add_f32_e32 v108, v89, v109
	v_mul_f32_e32 v108, 0xbfb8aa3b, v108
	v_exp_f32_e32 v108, v108
	v_add_f32_e32 v3, 1.0, v3
	v_rcp_f32_e32 v3, v3
	v_add_f32_e32 v110, v90, v110
	v_add_f32_e32 v108, 1.0, v108
	v_mul_f32_e32 v110, 0xbfb8aa3b, v110
	v_rcp_f32_e32 v109, v108
	v_exp_f32_e32 v110, v110
	v_add_f32_e32 v111, v91, v111
	v_mul_f32_e32 v111, 0xbfb8aa3b, v111

	v_exp_f32_e32 v111, v111

	v_mul_f32_e32 v108, v244, v3

	v_add_f32_e32 v110, 1.0, v110

	v_rcp_f32_e32 v110, v110
	v_mul_f32_e32 v109, v245, v109
	v_add_f32_e32 v3, 1.0, v111
	v_rcp_f32_e32 v3, v3


	v_mul_f32_e32 v110, v246, v110


	v_mul_f32_e32 v111, v247, v3
	ds_write_b128 v2, v[108:111] offset:12352
	v_lshlrev_b32_e32 v3, 2, v0
	v_lshlrev_b32_e32 v108, 4, v0


	v_and_b32_e32 v2, 60, v3
	v_and_b32_e32 v109, 0xffffc000, v108
	v_lshlrev_b32_e32 v2, 2, v2
	v_add_u32_e32 v109, 0, v109
	v_and_b32_e32 v108, 0x3f00, v108
	v_add3_u32 v128, v109, v108, v2
	v_xor_b32_e32 v128, v200, v128
	s_waitcnt lgkmcnt(0)
	s_barrier
	ds_read_b128 v[120:123], v128 offset:25600
	ds_read_b128 v[112:115], v128 offset:58368
	v_add_u32_e32 v127, 0, v2
	v_add_u32_e32 v129, v127, v108
	ds_read_b128 v[116:119], v129
	s_waitcnt lgkmcnt(2)
	v_mul_f32_e32 v108, 0x3fb8aa3b, v120
	v_exp_f32_e32 v108, v108
	v_add_f32_e32 v109, v120, v120
	v_cmp_nlt_f32_e32 vcc, s75, v109
	s_and_saveexec_b64 s[6:7], vcc
	s_xor_b64 s[6:7], exec, s[6:7]
	v_fma_f32 v120, -v108, v108, 1.0
	s_andn2_saveexec_b64 s[6:7], s[6:7]
	v_fmamk_f32 v110, v109, 0x3c088889, v125
	v_fmaak_f32 v110, v109, v110, 0x3e2aaaab
	v_fma_f32 v110, v109, v110, 0.5
	v_fma_f32 v110, v109, v110, 1.0
	v_mul_f32_e64 v120, v110, -v109
	s_or_b64 exec, exec, s[6:7]
	v_mul_f32_e32 v109, 0x3fb8aa3b, v121
	v_exp_f32_e32 v109, v109
	v_add_f32_e32 v110, v121, v121
	v_cmp_nlt_f32_e32 vcc, s75, v110
	s_and_saveexec_b64 s[6:7], vcc
	s_xor_b64 s[6:7], exec, s[6:7]
	v_fma_f32 v121, -v109, v109, 1.0
	s_andn2_saveexec_b64 s[6:7], s[6:7]
	v_fmamk_f32 v111, v110, 0x3c088889, v125
	v_fmaak_f32 v111, v110, v111, 0x3e2aaaab
	v_fma_f32 v111, v110, v111, 0.5
	v_fma_f32 v111, v110, v111, 1.0
	v_mul_f32_e64 v121, v111, -v110
	s_or_b64 exec, exec, s[6:7]
	v_mul_f32_e32 v110, 0x3fb8aa3b, v122
	v_exp_f32_e32 v110, v110
	v_add_f32_e32 v111, v122, v122
	v_cmp_nlt_f32_e32 vcc, s75, v111
	s_and_saveexec_b64 s[6:7], vcc
	s_xor_b64 s[6:7], exec, s[6:7]
	v_fma_f32 v122, -v110, v110, 1.0
	s_andn2_saveexec_b64 s[6:7], s[6:7]
	v_fmamk_f32 v122, v111, 0x3c088889, v125
	v_fmaak_f32 v122, v111, v122, 0x3e2aaaab
	v_fma_f32 v122, v111, v122, 0.5
	v_fma_f32 v122, v111, v122, 1.0
	v_mul_f32_e64 v122, v122, -v111
	s_or_b64 exec, exec, s[6:7]
	v_mul_f32_e32 v111, 0x3fb8aa3b, v123
	v_exp_f32_e32 v111, v111
	v_add_f32_e32 v130, v123, v123
	v_cmp_nlt_f32_e32 vcc, s75, v130
	s_and_saveexec_b64 s[6:7], vcc
	s_xor_b64 s[6:7], exec, s[6:7]
	v_fma_f32 v123, -v111, v111, 1.0
	s_andn2_saveexec_b64 s[6:7], s[6:7]
	v_fmamk_f32 v123, v130, 0x3c088889, v125
	v_fmaak_f32 v123, v130, v123, 0x3e2aaaab
	v_fma_f32 v123, v130, v123, 0.5
	v_fma_f32 v123, v130, v123, 1.0
	v_mul_f32_e64 v123, v123, -v130
	s_or_b64 exec, exec, s[6:7]
	v_max_f32_e32 v120, v120, v120
	v_max_f32_e32 v120, 0, v120
	v_sqrt_f32_e32 v120, v120
	v_max_f32_e32 v121, v121, v121
	v_max_f32_e32 v121, 0, v121
	v_sqrt_f32_e32 v121, v121
	s_waitcnt lgkmcnt(1)
	v_mul_f32_e32 v112, v112, v120
	s_waitcnt lgkmcnt(0)
	v_mul_f32_e32 v112, v116, v112
	v_max_f32_e32 v116, v122, v122
	v_max_f32_e32 v120, v123, v123
	v_max_f32_e32 v116, 0, v116
	v_max_f32_e32 v120, 0, v120
	v_sqrt_f32_e32 v116, v116
	v_sqrt_f32_e32 v120, v120
	v_mul_f32_e32 v113, v113, v121
	v_mul_f32_e32 v113, v117, v113
	v_mul_f32_e32 v114, v114, v116
	v_mul_f32_e32 v115, v115, v120
	v_mul_f32_e32 v114, v118, v114
	v_mul_f32_e32 v115, v119, v115
	ds_write_b128 v128, v[108:111] offset:25600
	ds_write_b128 v128, v[112:115] offset:58368
	v_add_u32_e32 v108, 0x800, v3
	v_and_b32_e32 v109, 0x3ffff000, v108
	v_and_b32_e32 v108, 0xfc0, v108
	v_lshl_add_u32 v109, v109, 2, 0
	v_lshlrev_b32_e32 v108, 2, v108
	v_add3_u32 v130, v109, v108, v2
	v_xor_b32_e32 v130, v200, v130
	ds_read_b128 v[120:123], v130 offset:25600
	ds_read_b128 v[112:115], v130 offset:58368
	v_add_u32_e32 v108, v127, v108
	ds_read_b128 v[116:119], v108
	s_waitcnt lgkmcnt(2)
	v_mul_f32_e32 v108, 0x3fb8aa3b, v120
	v_exp_f32_e32 v108, v108
	v_add_f32_e32 v109, v120, v120
	v_cmp_nlt_f32_e32 vcc, s75, v109
	s_and_saveexec_b64 s[6:7], vcc
	s_xor_b64 s[6:7], exec, s[6:7]
	v_fma_f32 v120, -v108, v108, 1.0
	s_andn2_saveexec_b64 s[6:7], s[6:7]
	v_fmamk_f32 v110, v109, 0x3c088889, v125
	v_fmaak_f32 v110, v109, v110, 0x3e2aaaab
	v_fma_f32 v110, v109, v110, 0.5
	v_fma_f32 v110, v109, v110, 1.0
	v_mul_f32_e64 v120, v110, -v109
	s_or_b64 exec, exec, s[6:7]
	v_mul_f32_e32 v109, 0x3fb8aa3b, v121
	v_exp_f32_e32 v109, v109
	v_add_f32_e32 v110, v121, v121
	v_cmp_nlt_f32_e32 vcc, s75, v110
	s_and_saveexec_b64 s[6:7], vcc
	s_xor_b64 s[6:7], exec, s[6:7]
	v_fma_f32 v121, -v109, v109, 1.0
	s_andn2_saveexec_b64 s[6:7], s[6:7]
	v_fmamk_f32 v111, v110, 0x3c088889, v125
	v_fmaak_f32 v111, v110, v111, 0x3e2aaaab
	v_fma_f32 v111, v110, v111, 0.5
	v_fma_f32 v111, v110, v111, 1.0
	v_mul_f32_e64 v121, v111, -v110
	s_or_b64 exec, exec, s[6:7]
	v_mul_f32_e32 v110, 0x3fb8aa3b, v122
	v_exp_f32_e32 v110, v110
	v_add_f32_e32 v111, v122, v122
	v_cmp_nlt_f32_e32 vcc, s75, v111
	s_and_saveexec_b64 s[6:7], vcc
	s_xor_b64 s[6:7], exec, s[6:7]
	v_fma_f32 v122, -v110, v110, 1.0
	s_andn2_saveexec_b64 s[6:7], s[6:7]
	v_fmamk_f32 v122, v111, 0x3c088889, v125
	v_fmaak_f32 v122, v111, v122, 0x3e2aaaab
	v_fma_f32 v122, v111, v122, 0.5
	v_fma_f32 v122, v111, v122, 1.0
	v_mul_f32_e64 v122, v122, -v111
	s_or_b64 exec, exec, s[6:7]
	v_mul_f32_e32 v111, 0x3fb8aa3b, v123
	v_exp_f32_e32 v111, v111
	v_add_f32_e32 v131, v123, v123
	v_cmp_nlt_f32_e32 vcc, s75, v131
	s_and_saveexec_b64 s[6:7], vcc
	s_xor_b64 s[6:7], exec, s[6:7]
	v_fma_f32 v123, -v111, v111, 1.0
	s_andn2_saveexec_b64 s[6:7], s[6:7]
	v_fmamk_f32 v123, v131, 0x3c088889, v125
	v_fmaak_f32 v123, v131, v123, 0x3e2aaaab
	v_fma_f32 v123, v131, v123, 0.5
	v_fma_f32 v123, v131, v123, 1.0
	v_mul_f32_e64 v123, v123, -v131
	s_or_b64 exec, exec, s[6:7]
	v_max_f32_e32 v120, v120, v120
	v_max_f32_e32 v120, 0, v120
	v_sqrt_f32_e32 v120, v120
	v_max_f32_e32 v121, v121, v121
	v_max_f32_e32 v121, 0, v121
	v_sqrt_f32_e32 v121, v121
	s_waitcnt lgkmcnt(1)
	v_mul_f32_e32 v112, v112, v120
	s_waitcnt lgkmcnt(0)
	v_mul_f32_e32 v112, v116, v112
	v_max_f32_e32 v116, v122, v122
	v_max_f32_e32 v120, v123, v123
	v_max_f32_e32 v116, 0, v116
	v_max_f32_e32 v120, 0, v120
	v_sqrt_f32_e32 v116, v116
	v_sqrt_f32_e32 v120, v120
	v_mul_f32_e32 v113, v113, v121
	v_mul_f32_e32 v113, v117, v113
	v_mul_f32_e32 v114, v114, v116
	v_mul_f32_e32 v115, v115, v120
	v_mul_f32_e32 v114, v118, v114
	v_mul_f32_e32 v115, v119, v115
	ds_write_b128 v130, v[108:111] offset:25600
	ds_write_b128 v130, v[112:115] offset:58368
	ds_read_b128 v[120:123], v128 offset:41984
	v_add_u32_e32 v130, 0xe400, v128
	ds_read_b128 v[112:115], v130 offset:16384
	ds_read_b128 v[116:119], v129
	s_waitcnt lgkmcnt(2)
	v_mul_f32_e32 v108, 0x3fb8aa3b, v120
	v_exp_f32_e32 v108, v108
	v_add_f32_e32 v109, v120, v120
	v_cmp_nlt_f32_e32 vcc, s75, v109
	s_and_saveexec_b64 s[6:7], vcc
	s_xor_b64 s[6:7], exec, s[6:7]
	v_fma_f32 v120, -v108, v108, 1.0
	s_andn2_saveexec_b64 s[6:7], s[6:7]
	v_fmamk_f32 v110, v109, 0x3c088889, v125
	v_fmaak_f32 v110, v109, v110, 0x3e2aaaab
	v_fma_f32 v110, v109, v110, 0.5
	v_fma_f32 v110, v109, v110, 1.0
	v_mul_f32_e64 v120, v110, -v109
	s_or_b64 exec, exec, s[6:7]
	v_mul_f32_e32 v109, 0x3fb8aa3b, v121
	v_exp_f32_e32 v109, v109
	v_add_f32_e32 v110, v121, v121
	v_cmp_nlt_f32_e32 vcc, s75, v110
	s_and_saveexec_b64 s[6:7], vcc
	s_xor_b64 s[6:7], exec, s[6:7]
	v_fma_f32 v121, -v109, v109, 1.0
	s_andn2_saveexec_b64 s[6:7], s[6:7]
	v_fmamk_f32 v111, v110, 0x3c088889, v125
	v_fmaak_f32 v111, v110, v111, 0x3e2aaaab
	v_fma_f32 v111, v110, v111, 0.5
	v_fma_f32 v111, v110, v111, 1.0
	v_mul_f32_e64 v121, v111, -v110
	s_or_b64 exec, exec, s[6:7]
	v_mul_f32_e32 v110, 0x3fb8aa3b, v122
	v_exp_f32_e32 v110, v110
	v_add_f32_e32 v111, v122, v122
	v_cmp_nlt_f32_e32 vcc, s75, v111
	s_and_saveexec_b64 s[6:7], vcc
	s_xor_b64 s[6:7], exec, s[6:7]
	v_fma_f32 v122, -v110, v110, 1.0
	s_andn2_saveexec_b64 s[6:7], s[6:7]
	v_fmamk_f32 v122, v111, 0x3c088889, v125
	v_fmaak_f32 v122, v111, v122, 0x3e2aaaab
	v_fma_f32 v122, v111, v122, 0.5
	v_fma_f32 v122, v111, v122, 1.0
	v_mul_f32_e64 v122, v122, -v111
	s_or_b64 exec, exec, s[6:7]
	v_mul_f32_e32 v111, 0x3fb8aa3b, v123
	v_exp_f32_e32 v111, v111
	v_add_f32_e32 v129, v123, v123
	v_cmp_nlt_f32_e32 vcc, s75, v129
	s_and_saveexec_b64 s[6:7], vcc
	s_xor_b64 s[6:7], exec, s[6:7]
	v_fma_f32 v123, -v111, v111, 1.0
	s_andn2_saveexec_b64 s[6:7], s[6:7]
	v_fmamk_f32 v123, v129, 0x3c088889, v125
	v_fmaak_f32 v123, v129, v123, 0x3e2aaaab
	v_fma_f32 v123, v129, v123, 0.5
	v_fma_f32 v123, v129, v123, 1.0
	v_mul_f32_e64 v123, v123, -v129
	s_or_b64 exec, exec, s[6:7]
	v_max_f32_e32 v120, v120, v120
	v_max_f32_e32 v120, 0, v120
	v_sqrt_f32_e32 v120, v120
	v_max_f32_e32 v121, v121, v121
	v_max_f32_e32 v121, 0, v121
	v_sqrt_f32_e32 v121, v121
	s_waitcnt lgkmcnt(1)
	v_mul_f32_e32 v112, v112, v120
	s_waitcnt lgkmcnt(0)
	v_mul_f32_e32 v112, v116, v112
	v_max_f32_e32 v116, v122, v122
	v_max_f32_e32 v120, v123, v123
	v_max_f32_e32 v116, 0, v116
	v_max_f32_e32 v120, 0, v120
	v_sqrt_f32_e32 v116, v116
	v_sqrt_f32_e32 v120, v120
	v_mul_f32_e32 v113, v113, v121
	v_add_u32_e32 v3, 0x1800, v3
	v_mul_f32_e32 v114, v114, v116
	v_mul_f32_e32 v115, v115, v120
	v_mul_f32_e32 v113, v117, v113
	v_mul_f32_e32 v114, v118, v114
	v_mul_f32_e32 v115, v119, v115
	ds_write_b128 v128, v[108:111] offset:41984
	ds_write_b128 v130, v[112:115] offset:16384
	v_and_b32_e32 v108, 0x3ffff000, v3
	v_and_b32_e32 v3, 0xfc0, v3
	v_lshl_add_u32 v108, v108, 2, 0
	v_lshlrev_b32_e32 v3, 2, v3
	v_add3_u32 v2, v108, v3, v2
	v_xor_b32_e32 v2, v200, v2
	ds_read_b128 v[120:123], v2 offset:25600
	ds_read_b128 v[112:115], v2 offset:58368
	v_add_u32_e32 v3, v127, v3
	ds_read_b128 v[116:119], v3
	s_waitcnt lgkmcnt(2)
	v_mul_f32_e32 v3, 0x3fb8aa3b, v120
	v_exp_f32_e32 v108, v3
	v_add_f32_e32 v109, v120, v120
	v_cmp_nlt_f32_e32 vcc, s75, v109
	s_and_saveexec_b64 s[6:7], vcc
	s_xor_b64 s[6:7], exec, s[6:7]
	v_fma_f32 v3, -v108, v108, 1.0
	s_andn2_saveexec_b64 s[6:7], s[6:7]
	v_fmamk_f32 v3, v109, 0x3c088889, v125
	v_fmaak_f32 v3, v109, v3, 0x3e2aaaab
	v_fma_f32 v3, v109, v3, 0.5
	v_fma_f32 v3, v109, v3, 1.0
	v_mul_f32_e64 v3, v3, -v109
	s_or_b64 exec, exec, s[6:7]
	v_mul_f32_e32 v109, 0x3fb8aa3b, v121
	v_exp_f32_e32 v109, v109
	v_add_f32_e32 v110, v121, v121
	v_cmp_nlt_f32_e32 vcc, s75, v110
	s_and_saveexec_b64 s[6:7], vcc
	s_xor_b64 s[6:7], exec, s[6:7]
	v_fma_f32 v121, -v109, v109, 1.0
	s_andn2_saveexec_b64 s[6:7], s[6:7]
	v_fmamk_f32 v111, v110, 0x3c088889, v125
	v_fmaak_f32 v111, v110, v111, 0x3e2aaaab
	v_fma_f32 v111, v110, v111, 0.5
	v_fma_f32 v111, v110, v111, 1.0
	v_mul_f32_e64 v121, v111, -v110
	s_or_b64 exec, exec, s[6:7]
	v_mul_f32_e32 v110, 0x3fb8aa3b, v122
	v_exp_f32_e32 v110, v110
	v_add_f32_e32 v111, v122, v122
	v_cmp_nlt_f32_e32 vcc, s75, v111
	s_and_saveexec_b64 s[6:7], vcc
	s_xor_b64 s[6:7], exec, s[6:7]
	v_fma_f32 v122, -v110, v110, 1.0
	s_andn2_saveexec_b64 s[6:7], s[6:7]
	v_fmamk_f32 v120, v111, 0x3c088889, v125
	v_fmaak_f32 v120, v111, v120, 0x3e2aaaab
	v_fma_f32 v120, v111, v120, 0.5
	v_fma_f32 v120, v111, v120, 1.0
	v_mul_f32_e64 v122, v120, -v111
	s_or_b64 exec, exec, s[6:7]
	v_mul_f32_e32 v111, 0x3fb8aa3b, v123
	v_exp_f32_e32 v111, v111
	v_add_f32_e32 v120, v123, v123
	v_cmp_nlt_f32_e32 vcc, s75, v120
	s_and_saveexec_b64 s[6:7], vcc
	s_xor_b64 s[6:7], exec, s[6:7]
	v_fma_f32 v123, -v111, v111, 1.0
	s_andn2_saveexec_b64 s[6:7], s[6:7]
	v_fmamk_f32 v123, v120, 0x3c088889, v125
	v_fmaak_f32 v123, v120, v123, 0x3e2aaaab
	v_fma_f32 v123, v120, v123, 0.5
	v_fma_f32 v123, v120, v123, 1.0
	v_mul_f32_e64 v123, v123, -v120
	s_or_b64 exec, exec, s[6:7]
	v_max_f32_e32 v3, v3, v3
	v_max_f32_e32 v3, 0, v3
	v_sqrt_f32_e32 v3, v3
	v_max_f32_e32 v121, v121, v121
	v_max_f32_e32 v121, 0, v121
	v_mov_b32_e32 v120, 0
	s_waitcnt lgkmcnt(1)
	v_mul_f32_e32 v3, v112, v3
	v_sqrt_f32_e32 v112, v121
	v_max_f32_e32 v121, v122, v122
	v_max_f32_e32 v121, 0, v121
	v_sqrt_f32_e32 v121, v121
	s_waitcnt lgkmcnt(0)
	v_mul_f32_e32 v116, v116, v3
	v_mul_f32_e32 v3, v113, v112
	v_mul_f32_e32 v117, v117, v3
	v_mul_f32_e32 v3, v114, v121
	v_mul_f32_e32 v118, v118, v3
	v_max_f32_e32 v3, v123, v123
	v_max_f32_e32 v3, 0, v3
	v_sqrt_f32_e32 v3, v3
	v_ashrrev_i32_e32 v114, 7, v0
	v_and_b32_e32 v121, 0x7f, v0
	v_bfe_u32 v113, v0, 6, 1
	v_mul_f32_e32 v3, v115, v3
	v_mul_f32_e32 v119, v119, v3
	ds_write_b128 v2, v[108:111] offset:25600
	ds_write_b128 v2, v[116:119] offset:58368
	v_lshlrev_b32_e32 v2, 4, v114

	v_and_b32_e32 v112, 63, v0


	s_waitcnt lgkmcnt(0)
	s_barrier
	ds_read2st64_b32 v[116:117], v172 offset0:100 offset1:228


	ds_read2st64_b32 v[118:119], v173 offset0:100 offset1:228


	ds_read2st64_b32 v[122:123], v174 offset0:100 offset1:228


	ds_read2st64_b32 v[128:129], v175 offset0:100 offset1:228


	ds_read2st64_b32 v[130:131], v176 offset0:100 offset1:228


	ds_read2st64_b32 v[132:133], v177 offset0:100 offset1:228


	ds_read2st64_b32 v[134:135], v178 offset0:100 offset1:228


	ds_read2st64_b32 v[136:137], v179 offset0:100 offset1:228


	ds_read2st64_b32 v[138:139], v180 offset0:100 offset1:228


	ds_read2st64_b32 v[140:141], v181 offset0:100 offset1:228


	ds_read2st64_b32 v[108:109], v170 offset0:100 offset1:228


	ds_read2st64_b32 v[110:111], v171 offset0:100 offset1:228
	ds_read2st64_b32 v[142:143], v182 offset0:100 offset1:228


	s_waitcnt lgkmcnt(2)
	v_fma_f32 v109, 0, v108, v109
	ds_read2st64_b32 v[144:145], v183 offset0:100 offset1:228
	v_or_b32_e32 v115, 14, v2
	s_waitcnt lgkmcnt(2)
	v_mul_f32_e32 v108, v108, v110
	v_fmac_f32_e32 v111, v109, v110
	v_sub_u32_e32 v127, 63, v115
	v_mul_f32_e32 v108, v108, v116
	v_fmac_f32_e32 v117, v111, v116

	v_mul_f32_e32 v108, v108, v118
	v_fmac_f32_e32 v119, v117, v118

	v_mul_f32_e32 v108, v108, v122
	v_fmac_f32_e32 v123, v119, v122

	v_or_b32_e32 v2, 15, v2
	v_mul_f32_e32 v108, v108, v128
	v_fmac_f32_e32 v129, v123, v128
	ds_read2st64_b32 v[146:147], v184 offset0:100 offset1:228
	v_sub_u32_e32 v115, 63, v2
	v_mul_f32_e32 v108, v108, v130
	v_fmac_f32_e32 v131, v129, v130

	v_mul_f32_e32 v108, v108, v132
	v_fmac_f32_e32 v133, v131, v132

	v_mul_f32_e32 v108, v108, v134
	v_fmac_f32_e32 v135, v133, v134

	v_mul_f32_e32 v108, v108, v136
	v_fmac_f32_e32 v137, v135, v136
	ds_read2st64_b32 v[2:3], v185 offset0:100 offset1:228
	v_mul_f32_e32 v108, v108, v138
	v_fmac_f32_e32 v139, v137, v138
	v_mul_f32_e32 v108, v108, v140
	v_fmac_f32_e32 v141, v139, v140
	s_waitcnt lgkmcnt(3)
	v_mul_f32_e32 v108, v108, v142
	v_fmac_f32_e32 v143, v141, v142
	s_waitcnt lgkmcnt(2)
	v_mul_f32_e32 v108, v108, v144
	v_fmac_f32_e32 v145, v143, v144
	s_waitcnt lgkmcnt(1)
	v_mul_f32_e32 v108, v108, v146
	v_fmac_f32_e32 v147, v145, v146
	v_lshl_add_u32 v0, v0, 2, 0
	s_waitcnt lgkmcnt(0)
	v_mul_f32_e32 v108, v108, v2
	v_fmac_f32_e32 v3, v147, v2
	v_add_u32_e32 v2, 0x16400, v0
	v_add_u32_e32 v0, 0x16c00, v0
	ds_write_b32 v2, v108
	ds_write_b32 v0, v3
	v_cmp_lt_i32_e32 vcc, 0, v114
	v_mov_b32_e32 v0, 1.0
	v_lshl_add_u32 v2, v121, 2, 0
	s_waitcnt vmcnt(0) lgkmcnt(0)
	s_barrier
	s_and_saveexec_b64 s[6:7], vcc
	s_cbranch_execnz .LBB0_434
	s_or_b64 exec, exec, s[6:7]
	v_cmp_lt_i32_e32 vcc, 1, v114
	s_and_saveexec_b64 s[6:7], vcc
	s_cbranch_execnz .LBB0_435
